# stack2 + early buffer_wbl2 by the last 1 non-leader arriver (K=1) at each grid barrier
# baseline (speedup 1.0000x reference)
; __device__ __forceinline__ unsigned xb_ld(unsigned* p)              { return __hip_atomic_load(p, __ATOMIC_RELAXED, __HIP_MEMORY_SCOPE_AGENT); }
; __device__ __forceinline__ unsigned xb_add(unsigned* p, unsigned v) { return __hip_atomic_fetch_add(p, v, __ATOMIC_RELAXED, __HIP_MEMORY_SCOPE_AGENT); }
; #define XB_SPIN(cond, bar) do { unsigned _sp = 0; while (cond) { __builtin_amdgcn_s_sleep(1); \
;     if ((++_sp & 255u) == 0u) { if (xb_ld(&(bar)[XB_TMO])) break; if (_sp > XB_SPIN_CAP) { atomicAdd(&(bar)[XB_TMO], 1u); break; } } } } while (0)
; __device__ __forceinline__ void xcd_barrier(const XcdBarrier& b) {
;     ...
;         const unsigned old = xb_add(&bar[XB_XSUB(b.x)], 1u);
;         const unsigned gen = old / nloc;
;         if (old + 1u == (gen + 1u) * nloc) {
;             __builtin_amdgcn_fence(__ATOMIC_RELEASE, "agent");
;             asm volatile("s_waitcnt vmcnt(0)" ::: "memory");
;             const unsigned og = xb_add(&bar[XB_TOP], 1u);
;             const unsigned tg = og / nx;
;             if (og + 1u == (tg + 1u) * nx) xb_add(&bar[XB_TOPGEN], 1u);
;             else XB_SPIN(xb_ld(&bar[XB_TOPGEN]) == tg, bar);
;             __builtin_amdgcn_fence(__ATOMIC_ACQUIRE, "agent");
;             xb_add(&bar[XB_XGEN(b.x)], 1u);
;             asm volatile("s_waitcnt vmcnt(0)" ::: "memory");
;         } else {
;             XB_SPIN(xb_ld(&bar[XB_XGEN(b.x)]) == gen, bar);
.LBB0_100:
	s_or_b64 exec, exec, s[10:11]
	v_cvt_f32_u32_e32 v5, v3
	s_waitcnt vmcnt(0)
	v_readfirstlane_b32 s8, v4
	v_sub_u32_e32 v4, 0, v3
	v_rcp_iflag_f32_e32 v5, v5
	v_add_u32_e32 v6, s8, v2
	v_mul_f32_e32 v5, 0x4f7ffffe, v5
	v_cvt_u32_f32_e32 v5, v5
	v_mul_lo_u32 v2, v4, v5
	v_mul_hi_u32 v2, v5, v2
	v_add_u32_e32 v2, v5, v2
	v_mul_hi_u32 v2, v6, v2
	v_mul_lo_u32 v4, v2, v3
	v_sub_u32_e32 v4, v6, v4
	v_add_u32_e32 v5, 1, v2
	v_cmp_ge_u32_e32 vcc, v4, v3
	s_nop 1
	v_cndmask_b32_e32 v2, v2, v5, vcc
	v_sub_u32_e32 v5, v4, v3
	v_cndmask_b32_e32 v4, v4, v5, vcc
	v_add_u32_e32 v5, 1, v2
	v_cmp_ge_u32_e32 vcc, v4, v3
	v_add_u32_e32 v4, 1, v6
	s_nop 0
	v_cndmask_b32_e32 v2, v2, v5, vcc
	v_mul_lo_u32 v5, v3, v2
	v_add_u32_e32 v3, v5, v3
	v_cmp_ne_u32_e32 vcc, v4, v3
	s_and_saveexec_b64 s[8:9], vcc
	s_xor_b64 s[8:9], exec, s[8:9]
	s_cbranch_execz .LBB0_114
	v_sub_u32_e32 v1, v3, v4
	s_nop 0
	v_readfirstlane_b32 s14, v1
	s_cmp_le_u32 s14, 1
	s_cbranch_scc0 .Lskip_wb0
	buffer_wbl2 sc1

; __device__ __forceinline__ unsigned xb_ld(unsigned* p)              { return __hip_atomic_load(p, __ATOMIC_RELAXED, __HIP_MEMORY_SCOPE_AGENT); }
; __device__ __forceinline__ unsigned xb_add(unsigned* p, unsigned v) { return __hip_atomic_fetch_add(p, v, __ATOMIC_RELAXED, __HIP_MEMORY_SCOPE_AGENT); }
; #define XB_SPIN(cond, bar) do { unsigned _sp = 0; while (cond) { __builtin_amdgcn_s_sleep(1); \
;     if ((++_sp & 255u) == 0u) { if (xb_ld(&(bar)[XB_TMO])) break; if (_sp > XB_SPIN_CAP) { atomicAdd(&(bar)[XB_TMO], 1u); break; } } } } while (0)
; __device__ __forceinline__ void xcd_barrier(const XcdBarrier& b) {
;     ...
;         const unsigned old = xb_add(&bar[XB_XSUB(b.x)], 1u);
;         const unsigned gen = old / nloc;
;         if (old + 1u == (gen + 1u) * nloc) {
;             __builtin_amdgcn_fence(__ATOMIC_RELEASE, "agent");
;             asm volatile("s_waitcnt vmcnt(0)" ::: "memory");
;             const unsigned og = xb_add(&bar[XB_TOP], 1u);
;             const unsigned tg = og / nx;
;             if (og + 1u == (tg + 1u) * nx) xb_add(&bar[XB_TOPGEN], 1u);
;             else XB_SPIN(xb_ld(&bar[XB_TOPGEN]) == tg, bar);
.LBB0_238:
	s_or_b64 exec, exec, s[12:13]
	v_cvt_f32_u32_e32 v6, v4
	s_waitcnt vmcnt(0)
	v_readfirstlane_b32 s3, v5
	v_sub_u32_e32 v5, 0, v4
	v_rcp_iflag_f32_e32 v6, v6
	v_add_u32_e32 v7, s3, v3
	v_mul_f32_e32 v6, 0x4f7ffffe, v6
	v_cvt_u32_f32_e32 v6, v6
	v_mul_lo_u32 v3, v5, v6
	v_mul_hi_u32 v3, v6, v3
	v_add_u32_e32 v3, v6, v3
	v_mul_hi_u32 v3, v7, v3
	v_mul_lo_u32 v5, v3, v4
	v_sub_u32_e32 v5, v7, v5
	v_add_u32_e32 v6, 1, v3
	v_cmp_ge_u32_e32 vcc, v5, v4
	s_nop 1
	v_cndmask_b32_e32 v3, v3, v6, vcc
	v_sub_u32_e32 v6, v5, v4
	v_cndmask_b32_e32 v5, v5, v6, vcc
	v_add_u32_e32 v6, 1, v3
	v_cmp_ge_u32_e32 vcc, v5, v4
	v_add_u32_e32 v5, 1, v7
	s_nop 0
	v_cndmask_b32_e32 v3, v3, v6, vcc
	v_mul_lo_u32 v6, v4, v3
	v_add_u32_e32 v4, v6, v4
	v_cmp_ne_u32_e32 vcc, v5, v4
	s_and_saveexec_b64 s[12:13], vcc
	s_xor_b64 s[18:19], exec, s[12:13]
	s_cbranch_execz .LBB0_252
	v_sub_u32_e32 v2, v4, v5
	s_nop 0
	v_readfirstlane_b32 s3, v2
	s_cmp_le_u32 s3, 1
	s_cbranch_scc0 .Lskip_wb1
	buffer_wbl2 sc1

; __device__ __forceinline__ unsigned xb_ld(unsigned* p)              { return __hip_atomic_load(p, __ATOMIC_RELAXED, __HIP_MEMORY_SCOPE_AGENT); }
; __device__ __forceinline__ unsigned xb_add(unsigned* p, unsigned v) { return __hip_atomic_fetch_add(p, v, __ATOMIC_RELAXED, __HIP_MEMORY_SCOPE_AGENT); }
; #define XB_SPIN(cond, bar) do { unsigned _sp = 0; while (cond) { __builtin_amdgcn_s_sleep(1); \
;     if ((++_sp & 255u) == 0u) { if (xb_ld(&(bar)[XB_TMO])) break; if (_sp > XB_SPIN_CAP) { atomicAdd(&(bar)[XB_TMO], 1u); break; } } } } while (0)
; __device__ __forceinline__ void xcd_barrier(const XcdBarrier& b) {
;     ...
;         const unsigned old = xb_add(&bar[XB_XSUB(b.x)], 1u);
;         const unsigned gen = old / nloc;
;         if (old + 1u == (gen + 1u) * nloc) {
;             __builtin_amdgcn_fence(__ATOMIC_RELEASE, "agent");
;             asm volatile("s_waitcnt vmcnt(0)" ::: "memory");
;             const unsigned og = xb_add(&bar[XB_TOP], 1u);
;             const unsigned tg = og / nx;
;             if (og + 1u == (tg + 1u) * nx) xb_add(&bar[XB_TOPGEN], 1u);
;             else XB_SPIN(xb_ld(&bar[XB_TOPGEN]) == tg, bar);
.LBB0_1022:
	s_or_b64 exec, exec, s[12:13]
	v_cvt_f32_u32_e32 v6, v4
	s_waitcnt vmcnt(0)
	v_readfirstlane_b32 s2, v5
	v_sub_u32_e32 v5, 0, v4
	v_rcp_iflag_f32_e32 v6, v6
	v_add_u32_e32 v7, s2, v3
	v_mul_f32_e32 v6, 0x4f7ffffe, v6
	v_cvt_u32_f32_e32 v6, v6
	v_mul_lo_u32 v3, v5, v6
	v_mul_hi_u32 v3, v6, v3
	v_add_u32_e32 v3, v6, v3
	v_mul_hi_u32 v3, v7, v3
	v_mul_lo_u32 v5, v3, v4
	v_sub_u32_e32 v5, v7, v5
	v_add_u32_e32 v6, 1, v3
	v_cmp_ge_u32_e32 vcc, v5, v4
	s_nop 1
	v_cndmask_b32_e32 v3, v3, v6, vcc
	v_sub_u32_e32 v6, v5, v4
	v_cndmask_b32_e32 v5, v5, v6, vcc
	v_add_u32_e32 v6, 1, v3
	v_cmp_ge_u32_e32 vcc, v5, v4
	v_add_u32_e32 v5, 1, v7
	s_nop 0
	v_cndmask_b32_e32 v3, v3, v6, vcc
	v_mul_lo_u32 v6, v4, v3
	v_add_u32_e32 v4, v6, v4
	v_cmp_ne_u32_e32 vcc, v5, v4
	s_and_saveexec_b64 s[2:3], vcc
	s_xor_b64 s[18:19], exec, s[2:3]
	s_cbranch_execz .LBB0_1036
	v_sub_u32_e32 v2, v4, v5
	s_nop 0
	v_readfirstlane_b32 s3, v2
	s_cmp_le_u32 s3, 1
	s_cbranch_scc0 .Lskip_wb8
	buffer_wbl2 sc1
